# GEMM K-loops: removed scalar no-ops (mid-block setprio pair, redundant lgkmcnt wait, s_nop behind m0 writes replaced by the address VALU)
# speedup vs baseline: 1.0061x; 1.0061x over previous
; #define PG8_STAGE(bufoff, gbase, voff) do { _Pragma("unroll") for (int _i = 0; _i < 2; ++_i) \
;         __builtin_amdgcn_global_load_lds((const unsigned*)((const char*)(gbase) + (voff)[_i]), (PG8_LAS unsigned*)(lds + (bufoff) + ldsw + _i * 8192), 16, 0, 0); } while (0)
; #define PG8_LDA(dst, b, h) do { _Pragma("unroll") for (int m = 0; m < 4; ++m) _Pragma("unroll") for (int k = 0; k < 2; ++k) dst[m][k] = *(const PG8_LAS bf16x8*)(lds + PG8_SA(b, h) + aoff + m * 2048 + k * 1024); } while (0)
; #define PG8_LDB(dst, b, h) do { _Pragma("unroll") for (int n = 0; n < 2; ++n) _Pragma("unroll") for (int k = 0; k < 2; ++k) dst[n][k] = *(const PG8_LAS bf16x8*)(lds + PG8_SB(b, h) + boff + n * 2048 + k * 1024); } while (0)
; #define PG8_MMA(ai, bj, At, Bt) do { __builtin_amdgcn_s_setprio(1); _Pragma("unroll") for (int m = 0; m < 4; ++m) _Pragma("unroll") for (int n = 0; n < 2; ++n) _Pragma("unroll") for (int k = 0; k < 2; ++k) \
;         acc[ai][bj][m][n] = __builtin_amdgcn_mfma_f32_16x16x32_bf16(Bt[n][k], At[m][k], acc[ai][bj][m][n], 0, 0, 0); __builtin_amdgcn_s_setprio(0); } while (0)
; #define PG8_WAIT_V(n) asm volatile("s_waitcnt vmcnt(" #n ")" ::: "memory")
; #define PG8_WAIT_L(n) asm volatile("s_waitcnt lgkmcnt(" #n ")" ::: "memory")
; #define PG8_BAR __builtin_amdgcn_s_barrier()
; #define PG8_SCHED __builtin_amdgcn_sched_barrier(0)
; template <class Epi, class Sched, bool ALIGN_EPI = false, bool SP2 = false>
; __device__ __forceinline__ void gemm_phase(PG8_LAS unsigned char* lds, const Gemm g, const Sched& S, const Epi& E) {
;     ...
;             if constexpr (SP2) {
;             PG8_LDB(B0, 0, 0); PG8_LDB(B1, 0, 1); PG8_SCHED; PG8_LDA(At, 0, 0); PG8_STAGE(PG8_SA(1, 1), a1 + hstep, voffA);
;             PG8_WAIT_V(8); PG8_WAIT_L(0); PG8_BAR; PG8_MMA(0, 0, At, B0); PG8_MMA(0, 1, At, B1); PG8_BAR; PG8_SCHED;
;             PG8_LDA(At, 0, 1); PG8_STAGE(PG8_SB(0, 0), b2, voffB); PG8_STAGE(PG8_SB(0, 1), b2 + hstep, voffB); PG8_STAGE(PG8_SA(0, 0), a2, voffA);
;             PG8_WAIT_V(8); PG8_WAIT_L(0); PG8_BAR; PG8_MMA(1, 0, At, B0); PG8_MMA(1, 1, At, B1); PG8_BAR; PG8_SCHED;
.LBB0_180:
	v_add_u32_e32 v142, s88, v177
	v_add_u32_e32 v168, s89, v177
	ds_read_b128 v[130:133], v142
	ds_read_b128 v[134:137], v142 offset:1024
	ds_read_b128 v[138:141], v142 offset:2048
	ds_read_b128 v[142:145], v142 offset:3072
	ds_read_b128 v[146:149], v168
	ds_read_b128 v[150:153], v168 offset:1024
	ds_read_b128 v[164:167], v168 offset:2048
	ds_read_b128 v[168:171], v168 offset:3072
	s_add_u32 s80, s78, 0xfff80080
	s_addc_u32 s81, s79, -1
	s_cmp_eq_u32 s52, 28
	s_cselect_b32 s83, s25, s81
	s_cselect_b32 s82, s27, s80
	s_cselect_b32 s81, s23, s51
	s_cselect_b32 s80, s37, s47
	v_lshl_add_u64 v[204:205], s[78:79], 0, v[160:161]
	s_add_i32 m0, s7, 0xc000
	ds_read_b128 v[172:175], v179
	ds_read_b128 v[180:183], v179 offset:1024
	ds_read_b128 v[184:187], v179 offset:2048
	ds_read_b128 v[188:191], v179 offset:3072
	ds_read_b128 v[192:195], v179 offset:4096
	ds_read_b128 v[196:199], v179 offset:5120
	ds_read_b128 v[200:203], v179 offset:6144
	ds_read_b128 v[208:211], v179 offset:7168
	global_load_lds_dwordx4 v[204:205], off
	s_add_i32 m0, s7, 0xe000
	v_lshl_add_u64 v[204:205], s[78:79], 0, v[162:163]
	global_load_lds_dwordx4 v[204:205], off
	s_waitcnt vmcnt(8)
	s_waitcnt lgkmcnt(0)
	s_barrier
	s_setprio 1
	v_mfma_f32_16x16x32_bf16 v[126:129], v[130:133], v[172:175], v[126:129]
	v_mfma_f32_16x16x32_bf16 v[122:125], v[138:141], v[172:175], v[122:125]
	v_mfma_f32_16x16x32_bf16 v[110:113], v[130:133], v[184:187], v[110:113]
	v_mfma_f32_16x16x32_bf16 v[106:109], v[138:141], v[184:187], v[106:109]
	v_mfma_f32_16x16x32_bf16 v[94:97], v[130:133], v[192:195], v[94:97]
	v_mfma_f32_16x16x32_bf16 v[90:93], v[138:141], v[192:195], v[90:93]
	v_mfma_f32_16x16x32_bf16 v[78:81], v[130:133], v[200:203], v[78:81]
	v_mfma_f32_16x16x32_bf16 v[74:77], v[138:141], v[200:203], v[74:77]
	v_mfma_f32_16x16x32_bf16 v[126:129], v[134:137], v[180:183], v[126:129]
	v_mfma_f32_16x16x32_bf16 v[122:125], v[142:145], v[180:183], v[122:125]
	v_mfma_f32_16x16x32_bf16 v[110:113], v[134:137], v[188:191], v[110:113]
	v_mfma_f32_16x16x32_bf16 v[106:109], v[142:145], v[188:191], v[106:109]
	v_mfma_f32_16x16x32_bf16 v[94:97], v[134:137], v[196:199], v[94:97]
	v_mfma_f32_16x16x32_bf16 v[90:93], v[142:145], v[196:199], v[90:93]
	v_mfma_f32_16x16x32_bf16 v[78:81], v[134:137], v[208:211], v[78:81]
	v_mfma_f32_16x16x32_bf16 v[74:77], v[142:145], v[208:211], v[74:77]
	v_mfma_f32_16x16x32_bf16 v[118:121], v[146:149], v[172:175], v[118:121]
	v_mfma_f32_16x16x32_bf16 v[114:117], v[164:167], v[172:175], v[114:117]
	v_mfma_f32_16x16x32_bf16 v[102:105], v[146:149], v[184:187], v[102:105]
	v_mfma_f32_16x16x32_bf16 v[98:101], v[164:167], v[184:187], v[98:101]
	v_mfma_f32_16x16x32_bf16 v[86:89], v[146:149], v[192:195], v[86:89]
	v_mfma_f32_16x16x32_bf16 v[82:85], v[164:167], v[192:195], v[82:85]
	v_mfma_f32_16x16x32_bf16 v[70:73], v[146:149], v[200:203], v[70:73]
	v_mfma_f32_16x16x32_bf16 v[66:69], v[164:167], v[200:203], v[66:69]
	v_mfma_f32_16x16x32_bf16 v[118:121], v[150:153], v[180:183], v[118:121]
	v_mfma_f32_16x16x32_bf16 v[114:117], v[168:171], v[180:183], v[114:117]
	v_mfma_f32_16x16x32_bf16 v[102:105], v[150:153], v[188:191], v[102:105]
	v_mfma_f32_16x16x32_bf16 v[98:101], v[168:171], v[188:191], v[98:101]
	v_mfma_f32_16x16x32_bf16 v[86:89], v[150:153], v[196:199], v[86:89]
	v_mfma_f32_16x16x32_bf16 v[82:85], v[168:171], v[196:199], v[82:85]
	v_mfma_f32_16x16x32_bf16 v[70:73], v[150:153], v[208:211], v[70:73]
	v_mfma_f32_16x16x32_bf16 v[66:69], v[168:171], v[208:211], v[66:69]
	s_setprio 0
	s_barrier
	s_add_i32 s84, s88, s6
	v_lshl_add_u64 v[204:205], s[80:81], 0, v[0:1]
	s_mov_b32 m0, s84
	ds_read_b128 v[172:175], v179 offset:16384
	ds_read_b128 v[180:183], v179 offset:17408
	ds_read_b128 v[184:187], v179 offset:18432
	ds_read_b128 v[188:191], v179 offset:19456
	ds_read_b128 v[192:195], v179 offset:20480
	ds_read_b128 v[196:199], v179 offset:21504
	ds_read_b128 v[200:203], v179 offset:22528
	ds_read_b128 v[208:211], v179 offset:23552
	global_load_lds_dwordx4 v[204:205], off
	s_add_i32 m0, s84, 0x2000
	s_add_u32 s84, s80, 0x80000
	v_lshl_add_u64 v[212:213], s[80:81], 0, v[158:159]
	s_addc_u32 s85, s81, 0
	s_add_i32 s86, s89, s6
	global_load_lds_dwordx4 v[212:213], off
	v_lshl_add_u64 v[230:231], s[84:85], 0, v[0:1]
	s_mov_b32 m0, s86
	v_lshl_add_u64 v[232:233], s[82:83], 0, v[156:157]
	global_load_lds_dwordx4 v[230:231], off
	s_add_i32 m0, s86, 0x2000
	v_lshl_add_u64 v[230:231], s[84:85], 0, v[158:159]
	global_load_lds_dwordx4 v[230:231], off
	s_mov_b32 m0, s7
	v_lshl_add_u64 v[230:231], s[82:83], 0, v[154:155]
	global_load_lds_dwordx4 v[230:231], off
	s_mov_b32 m0, s8
	s_nop 0
	global_load_lds_dwordx4 v[232:233], off
	s_waitcnt vmcnt(8)
	s_waitcnt lgkmcnt(0)
	s_barrier
; #define PG8_STAGE(bufoff, gbase, voff) do { _Pragma("unroll") for (int _i = 0; _i < 2; ++_i) \
;         __builtin_amdgcn_global_load_lds((const unsigned*)((const char*)(gbase) + (voff)[_i]), (PG8_LAS unsigned*)(lds + (bufoff) + ldsw + _i * 8192), 16, 0, 0); } while (0)
; #define PG8_LDA(dst, b, h) do { _Pragma("unroll") for (int m = 0; m < 4; ++m) _Pragma("unroll") for (int k = 0; k < 2; ++k) dst[m][k] = *(const PG8_LAS bf16x8*)(lds + PG8_SA(b, h) + aoff + m * 2048 + k * 1024); } while (0)
; #define PG8_LDB(dst, b, h) do { _Pragma("unroll") for (int n = 0; n < 2; ++n) _Pragma("unroll") for (int k = 0; k < 2; ++k) dst[n][k] = *(const PG8_LAS bf16x8*)(lds + PG8_SB(b, h) + boff + n * 2048 + k * 1024); } while (0)
; #define PG8_MMA(ai, bj, At, Bt) do { __builtin_amdgcn_s_setprio(1); _Pragma("unroll") for (int m = 0; m < 4; ++m) _Pragma("unroll") for (int n = 0; n < 2; ++n) _Pragma("unroll") for (int k = 0; k < 2; ++k) \
;         acc[ai][bj][m][n] = __builtin_amdgcn_mfma_f32_16x16x32_bf16(Bt[n][k], At[m][k], acc[ai][bj][m][n], 0, 0, 0); __builtin_amdgcn_s_setprio(0); } while (0)
; #define PG8_WAIT_V(n) asm volatile("s_waitcnt vmcnt(" #n ")" ::: "memory")
; #define PG8_WAIT_L(n) asm volatile("s_waitcnt lgkmcnt(" #n ")" ::: "memory")
; #define PG8_BAR __builtin_amdgcn_s_barrier()
; #define PG8_SCHED __builtin_amdgcn_sched_barrier(0)
; template <class Epi, class Sched, bool ALIGN_EPI = false, bool SP2 = false>
; __device__ __forceinline__ void gemm_phase(PG8_LAS unsigned char* lds, const Gemm g, const Sched& S, const Epi& E) {
;     ...
;             PG8_WAIT_V(8); PG8_WAIT_L(0); PG8_BAR; PG8_MMA(0, 0, At, B0); PG8_MMA(0, 1, At, B1); PG8_BAR; PG8_SCHED;
;             PG8_LDA(At, 0, 1); PG8_STAGE(PG8_SB(0, 0), b2, voffB); PG8_STAGE(PG8_SB(0, 1), b2 + hstep, voffB); PG8_STAGE(PG8_SA(0, 0), a2, voffA);
;             PG8_WAIT_V(8); PG8_WAIT_L(0); PG8_BAR; PG8_MMA(1, 0, At, B0); PG8_MMA(1, 1, At, B1); PG8_BAR; PG8_SCHED;
;             PG8_LDB(B0, 1, 0); PG8_LDB(B1, 1, 1); PG8_SCHED; PG8_LDA(At, 1, 0); PG8_STAGE(PG8_SA(0, 1), a2 + hstep, voffA);
;             PG8_WAIT_V(8); PG8_WAIT_L(0); PG8_BAR; PG8_MMA(0, 0, At, B0); PG8_MMA(0, 1, At, B1); PG8_BAR; PG8_SCHED;
	s_setprio 1
	v_mfma_f32_16x16x32_bf16 v[62:65], v[130:133], v[172:175], v[62:65]
	v_mfma_f32_16x16x32_bf16 v[58:61], v[138:141], v[172:175], v[58:61]
	v_mfma_f32_16x16x32_bf16 v[46:49], v[130:133], v[184:187], v[46:49]
	v_mfma_f32_16x16x32_bf16 v[42:45], v[138:141], v[184:187], v[42:45]
	v_mfma_f32_16x16x32_bf16 v[30:33], v[130:133], v[192:195], v[30:33]
	v_mfma_f32_16x16x32_bf16 v[26:29], v[138:141], v[192:195], v[26:29]
	v_mfma_f32_16x16x32_bf16 v[14:17], v[130:133], v[200:203], v[14:17]
	v_mfma_f32_16x16x32_bf16 v[10:13], v[138:141], v[200:203], v[10:13]
	v_mfma_f32_16x16x32_bf16 v[62:65], v[134:137], v[180:183], v[62:65]
	v_mfma_f32_16x16x32_bf16 v[58:61], v[142:145], v[180:183], v[58:61]
	v_mfma_f32_16x16x32_bf16 v[46:49], v[134:137], v[188:191], v[46:49]
	v_mfma_f32_16x16x32_bf16 v[42:45], v[142:145], v[188:191], v[42:45]
	v_mfma_f32_16x16x32_bf16 v[30:33], v[134:137], v[196:199], v[30:33]
	v_mfma_f32_16x16x32_bf16 v[26:29], v[142:145], v[196:199], v[26:29]
	v_mfma_f32_16x16x32_bf16 v[14:17], v[134:137], v[208:211], v[14:17]
	v_mfma_f32_16x16x32_bf16 v[10:13], v[142:145], v[208:211], v[10:13]
	v_mfma_f32_16x16x32_bf16 v[54:57], v[146:149], v[172:175], v[54:57]
	v_mfma_f32_16x16x32_bf16 v[50:53], v[164:167], v[172:175], v[50:53]
	v_mfma_f32_16x16x32_bf16 v[38:41], v[146:149], v[184:187], v[38:41]
	v_mfma_f32_16x16x32_bf16 v[34:37], v[164:167], v[184:187], v[34:37]
	v_mfma_f32_16x16x32_bf16 v[22:25], v[146:149], v[192:195], v[22:25]
	v_mfma_f32_16x16x32_bf16 v[18:21], v[164:167], v[192:195], v[18:21]
	v_mfma_f32_16x16x32_bf16 v[6:9], v[146:149], v[200:203], v[6:9]
	v_mfma_f32_16x16x32_bf16 v[2:5], v[164:167], v[200:203], v[2:5]
	v_mfma_f32_16x16x32_bf16 v[54:57], v[150:153], v[180:183], v[54:57]
	v_mfma_f32_16x16x32_bf16 v[50:53], v[168:171], v[180:183], v[50:53]
	v_mfma_f32_16x16x32_bf16 v[38:41], v[150:153], v[188:191], v[38:41]
	v_mfma_f32_16x16x32_bf16 v[34:37], v[168:171], v[188:191], v[34:37]
	v_mfma_f32_16x16x32_bf16 v[22:25], v[150:153], v[196:199], v[22:25]
	v_mfma_f32_16x16x32_bf16 v[18:21], v[168:171], v[196:199], v[18:21]
	v_mfma_f32_16x16x32_bf16 v[6:9], v[150:153], v[208:211], v[6:9]
	v_mfma_f32_16x16x32_bf16 v[2:5], v[168:171], v[208:211], v[2:5]
	s_setprio 0
	s_barrier
	s_add_i32 s84, 0, 0x1c000
	v_add_u32_e32 v142, s90, v177
	v_add_u32_e32 v168, s84, v177
	ds_read_b128 v[130:133], v142
	ds_read_b128 v[134:137], v142 offset:1024
	ds_read_b128 v[138:141], v142 offset:2048
	ds_read_b128 v[142:145], v142 offset:3072
	ds_read_b128 v[146:149], v168
	ds_read_b128 v[150:153], v168 offset:1024
	ds_read_b128 v[164:167], v168 offset:2048
	ds_read_b128 v[168:171], v168 offset:3072
	s_add_u32 s82, s82, 0x80000
	s_addc_u32 s83, s83, 0
	s_mov_b32 m0, s9
	v_lshl_add_u64 v[234:235], s[82:83], 0, v[154:155]
	ds_read_b128 v[172:175], v179 offset:32768
	ds_read_b128 v[180:183], v179 offset:33792
	ds_read_b128 v[184:187], v179 offset:34816
	ds_read_b128 v[188:191], v179 offset:35840
	ds_read_b128 v[192:195], v179 offset:36864
	ds_read_b128 v[196:199], v179 offset:37888
	ds_read_b128 v[200:203], v179 offset:38912
	ds_read_b128 v[208:211], v179 offset:39936
	global_load_lds_dwordx4 v[234:235], off
	s_mov_b32 m0, s10
	v_lshl_add_u64 v[234:235], s[82:83], 0, v[156:157]
	global_load_lds_dwordx4 v[234:235], off
	s_waitcnt vmcnt(8)
	s_waitcnt lgkmcnt(0)
	s_barrier
	s_setprio 1
	v_mfma_f32_16x16x32_bf16 v[126:129], v[130:133], v[172:175], v[126:129]
	v_mfma_f32_16x16x32_bf16 v[122:125], v[138:141], v[172:175], v[122:125]
	v_mfma_f32_16x16x32_bf16 v[110:113], v[130:133], v[184:187], v[110:113]
	v_mfma_f32_16x16x32_bf16 v[106:109], v[138:141], v[184:187], v[106:109]
	v_mfma_f32_16x16x32_bf16 v[94:97], v[130:133], v[192:195], v[94:97]
	v_mfma_f32_16x16x32_bf16 v[90:93], v[138:141], v[192:195], v[90:93]
	v_mfma_f32_16x16x32_bf16 v[78:81], v[130:133], v[200:203], v[78:81]
	v_mfma_f32_16x16x32_bf16 v[74:77], v[138:141], v[200:203], v[74:77]
	v_mfma_f32_16x16x32_bf16 v[126:129], v[134:137], v[180:183], v[126:129]
	v_mfma_f32_16x16x32_bf16 v[122:125], v[142:145], v[180:183], v[122:125]
	v_mfma_f32_16x16x32_bf16 v[110:113], v[134:137], v[188:191], v[110:113]
	v_mfma_f32_16x16x32_bf16 v[106:109], v[142:145], v[188:191], v[106:109]
	v_mfma_f32_16x16x32_bf16 v[94:97], v[134:137], v[196:199], v[94:97]
	v_mfma_f32_16x16x32_bf16 v[90:93], v[142:145], v[196:199], v[90:93]
	v_mfma_f32_16x16x32_bf16 v[78:81], v[134:137], v[208:211], v[78:81]
	v_mfma_f32_16x16x32_bf16 v[74:77], v[142:145], v[208:211], v[74:77]
	v_mfma_f32_16x16x32_bf16 v[118:121], v[146:149], v[172:175], v[118:121]
	v_mfma_f32_16x16x32_bf16 v[114:117], v[164:167], v[172:175], v[114:117]
	v_mfma_f32_16x16x32_bf16 v[102:105], v[146:149], v[184:187], v[102:105]
	v_mfma_f32_16x16x32_bf16 v[98:101], v[164:167], v[184:187], v[98:101]
	v_mfma_f32_16x16x32_bf16 v[86:89], v[146:149], v[192:195], v[86:89]
	v_mfma_f32_16x16x32_bf16 v[82:85], v[164:167], v[192:195], v[82:85]
	v_mfma_f32_16x16x32_bf16 v[70:73], v[146:149], v[200:203], v[70:73]
	v_mfma_f32_16x16x32_bf16 v[66:69], v[164:167], v[200:203], v[66:69]
	v_mfma_f32_16x16x32_bf16 v[118:121], v[150:153], v[180:183], v[118:121]
	v_mfma_f32_16x16x32_bf16 v[114:117], v[168:171], v[180:183], v[114:117]
	v_mfma_f32_16x16x32_bf16 v[102:105], v[150:153], v[188:191], v[102:105]
	v_mfma_f32_16x16x32_bf16 v[98:101], v[168:171], v[188:191], v[98:101]
	v_mfma_f32_16x16x32_bf16 v[86:89], v[150:153], v[196:199], v[86:89]
	v_mfma_f32_16x16x32_bf16 v[82:85], v[168:171], v[196:199], v[82:85]
	v_mfma_f32_16x16x32_bf16 v[70:73], v[150:153], v[208:211], v[70:73]
	v_mfma_f32_16x16x32_bf16 v[66:69], v[168:171], v[208:211], v[66:69]
	s_setprio 0
	s_barrier
; #define PG8_STAGE(bufoff, gbase, voff) do { _Pragma("unroll") for (int _i = 0; _i < 2; ++_i) \
;         __builtin_amdgcn_global_load_lds((const unsigned*)((const char*)(gbase) + (voff)[_i]), (PG8_LAS unsigned*)(lds + (bufoff) + ldsw + _i * 8192), 16, 0, 0); } while (0)
; #define PG8_LDA(dst, b, h) do { _Pragma("unroll") for (int m = 0; m < 4; ++m) _Pragma("unroll") for (int k = 0; k < 2; ++k) dst[m][k] = *(const PG8_LAS bf16x8*)(lds + PG8_SA(b, h) + aoff + m * 2048 + k * 1024); } while (0)
; #define PG8_MMA(ai, bj, At, Bt) do { __builtin_amdgcn_s_setprio(1); _Pragma("unroll") for (int m = 0; m < 4; ++m) _Pragma("unroll") for (int n = 0; n < 2; ++n) _Pragma("unroll") for (int k = 0; k < 2; ++k) \
;         acc[ai][bj][m][n] = __builtin_amdgcn_mfma_f32_16x16x32_bf16(Bt[n][k], At[m][k], acc[ai][bj][m][n], 0, 0, 0); __builtin_amdgcn_s_setprio(0); } while (0)
; #define PG8_WAIT_V(n) asm volatile("s_waitcnt vmcnt(" #n ")" ::: "memory")
; #define PG8_WAIT_L(n) asm volatile("s_waitcnt lgkmcnt(" #n ")" ::: "memory")
; #define PG8_BAR __builtin_amdgcn_s_barrier()
; #define PG8_SCHED __builtin_amdgcn_sched_barrier(0)
; template <class Epi, class Sched, bool ALIGN_EPI = false, bool SP2 = false>
; __device__ __forceinline__ void gemm_phase(PG8_LAS unsigned char* lds, const Gemm g, const Sched& S, const Epi& E) {
;     ...
;             PG8_WAIT_V(8); PG8_WAIT_L(0); PG8_BAR; PG8_MMA(0, 0, At, B0); PG8_MMA(0, 1, At, B1); PG8_BAR; PG8_SCHED;
;             PG8_LDA(At, 1, 1); PG8_STAGE(PG8_SB(1, 0), b3, voffB); PG8_STAGE(PG8_SB(1, 1), b3 + hstep, voffB); PG8_STAGE(PG8_SA(1, 0), a3, voffA);
;             PG8_WAIT_V(8); PG8_WAIT_L(0); PG8_BAR; PG8_MMA(1, 0, At, B0); PG8_MMA(1, 1, At, B1); PG8_BAR; PG8_SCHED;
;     ...
;         if constexpr (ALIGN_EPI) { if (wr == 0) PG8_BAR; }
	s_add_i32 s82, s90, s6
	v_lshl_add_u64 v[204:205], v[204:205], 0, s[70:71]
	s_mov_b32 m0, s82
	ds_read_b128 v[172:175], v179 offset:49152
	ds_read_b128 v[180:183], v179 offset:50176
	ds_read_b128 v[184:187], v179 offset:51200
	ds_read_b128 v[188:191], v179 offset:52224
	ds_read_b128 v[192:195], v179 offset:53248
	ds_read_b128 v[196:199], v179 offset:54272
	ds_read_b128 v[200:203], v179 offset:55296
	ds_read_b128 v[208:211], v179 offset:56320
	global_load_lds_dwordx4 v[204:205], off
	s_add_i32 m0, s82, 0x2000
	s_add_u32 s80, s80, 0x80080
	v_lshl_add_u64 v[204:205], v[212:213], 0, s[70:71]
	s_addc_u32 s81, s81, 0
	s_add_i32 s82, s84, s6
	global_load_lds_dwordx4 v[204:205], off
	s_mov_b32 m0, s82
	v_lshl_add_u64 v[204:205], s[80:81], 0, v[0:1]
	global_load_lds_dwordx4 v[204:205], off
	s_add_i32 m0, s82, 0x2000
	v_lshl_add_u64 v[204:205], s[80:81], 0, v[158:159]
	global_load_lds_dwordx4 v[204:205], off
	s_mov_b32 m0, s12
	v_lshl_add_u64 v[204:205], v[230:231], 0, s[70:71]
	global_load_lds_dwordx4 v[204:205], off
	s_mov_b32 m0, s13
	v_lshl_add_u64 v[204:205], v[232:233], 0, s[70:71]
	global_load_lds_dwordx4 v[204:205], off
	s_waitcnt vmcnt(8)
	s_waitcnt lgkmcnt(0)
	s_barrier
	s_setprio 1
	v_mfma_f32_16x16x32_bf16 v[62:65], v[130:133], v[172:175], v[62:65]
	v_mfma_f32_16x16x32_bf16 v[58:61], v[138:141], v[172:175], v[58:61]
	v_mfma_f32_16x16x32_bf16 v[46:49], v[130:133], v[184:187], v[46:49]
	v_mfma_f32_16x16x32_bf16 v[42:45], v[138:141], v[184:187], v[42:45]
	v_mfma_f32_16x16x32_bf16 v[30:33], v[130:133], v[192:195], v[30:33]
	v_mfma_f32_16x16x32_bf16 v[26:29], v[138:141], v[192:195], v[26:29]
	v_mfma_f32_16x16x32_bf16 v[14:17], v[130:133], v[200:203], v[14:17]
	v_mfma_f32_16x16x32_bf16 v[10:13], v[138:141], v[200:203], v[10:13]
	v_mfma_f32_16x16x32_bf16 v[62:65], v[134:137], v[180:183], v[62:65]
	v_mfma_f32_16x16x32_bf16 v[58:61], v[142:145], v[180:183], v[58:61]
	v_mfma_f32_16x16x32_bf16 v[46:49], v[134:137], v[188:191], v[46:49]
	v_mfma_f32_16x16x32_bf16 v[42:45], v[142:145], v[188:191], v[42:45]
	v_mfma_f32_16x16x32_bf16 v[30:33], v[134:137], v[196:199], v[30:33]
	v_mfma_f32_16x16x32_bf16 v[26:29], v[142:145], v[196:199], v[26:29]
	v_mfma_f32_16x16x32_bf16 v[14:17], v[134:137], v[208:211], v[14:17]
	v_mfma_f32_16x16x32_bf16 v[10:13], v[142:145], v[208:211], v[10:13]
	v_mfma_f32_16x16x32_bf16 v[54:57], v[146:149], v[172:175], v[54:57]
	v_mfma_f32_16x16x32_bf16 v[50:53], v[164:167], v[172:175], v[50:53]
	v_mfma_f32_16x16x32_bf16 v[38:41], v[146:149], v[184:187], v[38:41]
	v_mfma_f32_16x16x32_bf16 v[34:37], v[164:167], v[184:187], v[34:37]
	v_mfma_f32_16x16x32_bf16 v[22:25], v[146:149], v[192:195], v[22:25]
	v_mfma_f32_16x16x32_bf16 v[18:21], v[164:167], v[192:195], v[18:21]
	v_mfma_f32_16x16x32_bf16 v[6:9], v[146:149], v[200:203], v[6:9]
	v_mfma_f32_16x16x32_bf16 v[2:5], v[164:167], v[200:203], v[2:5]
	v_mfma_f32_16x16x32_bf16 v[54:57], v[150:153], v[180:183], v[54:57]
	v_mfma_f32_16x16x32_bf16 v[50:53], v[168:171], v[180:183], v[50:53]
	v_mfma_f32_16x16x32_bf16 v[38:41], v[150:153], v[188:191], v[38:41]
	v_mfma_f32_16x16x32_bf16 v[34:37], v[168:171], v[188:191], v[34:37]
	v_mfma_f32_16x16x32_bf16 v[22:25], v[150:153], v[196:199], v[22:25]
	v_mfma_f32_16x16x32_bf16 v[18:21], v[168:171], v[196:199], v[18:21]
	v_mfma_f32_16x16x32_bf16 v[6:9], v[150:153], v[208:211], v[6:9]
	v_mfma_f32_16x16x32_bf16 v[2:5], v[168:171], v[208:211], v[2:5]
	s_setprio 0
	s_barrier
	s_add_i32 s52, s52, 2
	s_add_u32 s78, s78, 0x100
	s_addc_u32 s79, s79, 0
	s_add_u32 s47, s47, 0x100
	s_addc_u32 s51, s51, 0
	s_cmp_gt_u32 s52, 29
	s_cbranch_scc0 .LBB0_180
	s_and_b64 vcc, exec, s[18:19]
	s_cbranch_vccz .LBB0_183
	s_barrier

; #define PG8_STAGE(bufoff, gbase, voff) do { _Pragma("unroll") for (int _i = 0; _i < 2; ++_i) \
;         __builtin_amdgcn_global_load_lds((const unsigned*)((const char*)(gbase) + (voff)[_i]), (PG8_LAS unsigned*)(lds + (bufoff) + ldsw + _i * 8192), 16, 0, 0); } while (0)
; #define PG8_LDA(dst, b, h) do { _Pragma("unroll") for (int m = 0; m < 4; ++m) _Pragma("unroll") for (int k = 0; k < 2; ++k) dst[m][k] = *(const PG8_LAS bf16x8*)(lds + PG8_SA(b, h) + aoff + m * 2048 + k * 1024); } while (0)
; #define PG8_LDB(dst, b, h) do { _Pragma("unroll") for (int n = 0; n < 2; ++n) _Pragma("unroll") for (int k = 0; k < 2; ++k) dst[n][k] = *(const PG8_LAS bf16x8*)(lds + PG8_SB(b, h) + boff + n * 2048 + k * 1024); } while (0)
; #define PG8_MMA(ai, bj, At, Bt) do { __builtin_amdgcn_s_setprio(1); _Pragma("unroll") for (int m = 0; m < 4; ++m) _Pragma("unroll") for (int n = 0; n < 2; ++n) _Pragma("unroll") for (int k = 0; k < 2; ++k) \
;         acc[ai][bj][m][n] = __builtin_amdgcn_mfma_f32_16x16x32_bf16(Bt[n][k], At[m][k], acc[ai][bj][m][n], 0, 0, 0); __builtin_amdgcn_s_setprio(0); } while (0)
; #define PG8_WAIT_V(n) asm volatile("s_waitcnt vmcnt(" #n ")" ::: "memory")
; #define PG8_WAIT_L(n) asm volatile("s_waitcnt lgkmcnt(" #n ")" ::: "memory")
; #define PG8_BAR __builtin_amdgcn_s_barrier()
; #define PG8_SCHED __builtin_amdgcn_sched_barrier(0)
; template <class Epi, class Sched, bool ALIGN_EPI = false, bool SP2 = false>
; __device__ __forceinline__ void gemm_phase(PG8_LAS unsigned char* lds, const Gemm g, const Sched& S, const Epi& E) {
;     ...
;             if constexpr (SP2) {
;             PG8_LDB(B0, 0, 0); PG8_LDB(B1, 0, 1); PG8_SCHED; PG8_LDA(At, 0, 0); PG8_STAGE(PG8_SA(1, 1), a1 + hstep, voffA);
;             PG8_WAIT_V(8); PG8_WAIT_L(0); PG8_BAR; PG8_MMA(0, 0, At, B0); PG8_MMA(0, 1, At, B1); PG8_BAR; PG8_SCHED;
;             PG8_LDA(At, 0, 1); PG8_STAGE(PG8_SB(0, 0), b2, voffB); PG8_STAGE(PG8_SB(0, 1), b2 + hstep, voffB); PG8_STAGE(PG8_SA(0, 0), a2, voffA);
;             PG8_WAIT_V(8); PG8_WAIT_L(0); PG8_BAR; PG8_MMA(1, 0, At, B0); PG8_MMA(1, 1, At, B1); PG8_BAR; PG8_SCHED;
.LBB0_214:
	v_add_u32_e32 v134, s88, v177
	v_add_u32_e32 v172, s89, v177
	ds_read_b128 v[114:117], v134
	ds_read_b128 v[118:121], v134 offset:1024
	ds_read_b128 v[130:133], v134 offset:2048
	ds_read_b128 v[134:137], v134 offset:3072
	ds_read_b128 v[146:149], v172
	ds_read_b128 v[150:153], v172 offset:1024
	ds_read_b128 v[168:171], v172 offset:2048
	ds_read_b128 v[172:175], v172 offset:3072
	s_add_u32 s40, s34, 0xfff80080
	s_addc_u32 s41, s35, -1
	s_cmp_eq_u32 s46, 28
	s_cselect_b32 s43, s15, s41
	s_cselect_b32 s42, s19, s40
	s_cselect_b32 s41, s17, s45
	s_cselect_b32 s40, s37, s44
	v_lshl_add_u64 v[204:205], s[34:35], 0, v[164:165]
	s_add_i32 m0, s8, 0xc000
	ds_read_b128 v[180:183], v178
	ds_read_b128 v[184:187], v178 offset:1024
	ds_read_b128 v[188:191], v178 offset:2048
	ds_read_b128 v[192:195], v178 offset:3072
	ds_read_b128 v[196:199], v178 offset:4096
	ds_read_b128 v[200:203], v178 offset:5120
	ds_read_b128 v[208:211], v178 offset:6144
	ds_read_b128 v[230:233], v178 offset:7168
	global_load_lds_dwordx4 v[204:205], off
	s_add_i32 m0, s8, 0xe000
	v_lshl_add_u64 v[204:205], s[34:35], 0, v[166:167]
	global_load_lds_dwordx4 v[204:205], off
	s_waitcnt vmcnt(8)
	s_waitcnt lgkmcnt(0)
	s_barrier
	s_setprio 1
	v_mfma_f32_16x16x32_bf16 v[142:145], v[114:117], v[180:183], v[142:145]
	v_mfma_f32_16x16x32_bf16 v[138:141], v[130:133], v[180:183], v[138:141]
	v_mfma_f32_16x16x32_bf16 v[110:113], v[114:117], v[188:191], v[110:113]
	v_mfma_f32_16x16x32_bf16 v[106:109], v[130:133], v[188:191], v[106:109]
	v_mfma_f32_16x16x32_bf16 v[94:97], v[114:117], v[196:199], v[94:97]
	v_mfma_f32_16x16x32_bf16 v[90:93], v[130:133], v[196:199], v[90:93]
	v_mfma_f32_16x16x32_bf16 v[78:81], v[114:117], v[208:211], v[78:81]
	v_mfma_f32_16x16x32_bf16 v[74:77], v[130:133], v[208:211], v[74:77]
	v_mfma_f32_16x16x32_bf16 v[142:145], v[118:121], v[184:187], v[142:145]
	v_mfma_f32_16x16x32_bf16 v[138:141], v[134:137], v[184:187], v[138:141]
	v_mfma_f32_16x16x32_bf16 v[110:113], v[118:121], v[192:195], v[110:113]
	v_mfma_f32_16x16x32_bf16 v[106:109], v[134:137], v[192:195], v[106:109]
	v_mfma_f32_16x16x32_bf16 v[94:97], v[118:121], v[200:203], v[94:97]
	v_mfma_f32_16x16x32_bf16 v[90:93], v[134:137], v[200:203], v[90:93]
	v_mfma_f32_16x16x32_bf16 v[78:81], v[118:121], v[230:233], v[78:81]
	v_mfma_f32_16x16x32_bf16 v[74:77], v[134:137], v[230:233], v[74:77]
	v_mfma_f32_16x16x32_bf16 v[126:129], v[146:149], v[180:183], v[126:129]
	v_mfma_f32_16x16x32_bf16 v[122:125], v[168:171], v[180:183], v[122:125]
	v_mfma_f32_16x16x32_bf16 v[102:105], v[146:149], v[188:191], v[102:105]
	v_mfma_f32_16x16x32_bf16 v[98:101], v[168:171], v[188:191], v[98:101]
	v_mfma_f32_16x16x32_bf16 v[86:89], v[146:149], v[196:199], v[86:89]
	v_mfma_f32_16x16x32_bf16 v[82:85], v[168:171], v[196:199], v[82:85]
	v_mfma_f32_16x16x32_bf16 v[70:73], v[146:149], v[208:211], v[70:73]
	v_mfma_f32_16x16x32_bf16 v[66:69], v[168:171], v[208:211], v[66:69]
	v_mfma_f32_16x16x32_bf16 v[126:129], v[150:153], v[184:187], v[126:129]
	v_mfma_f32_16x16x32_bf16 v[122:125], v[172:175], v[184:187], v[122:125]
	v_mfma_f32_16x16x32_bf16 v[102:105], v[150:153], v[192:195], v[102:105]
	v_mfma_f32_16x16x32_bf16 v[98:101], v[172:175], v[192:195], v[98:101]
	v_mfma_f32_16x16x32_bf16 v[86:89], v[150:153], v[200:203], v[86:89]
	v_mfma_f32_16x16x32_bf16 v[82:85], v[172:175], v[200:203], v[82:85]
	v_mfma_f32_16x16x32_bf16 v[70:73], v[150:153], v[230:233], v[70:73]
	v_mfma_f32_16x16x32_bf16 v[66:69], v[172:175], v[230:233], v[66:69]
	s_setprio 0
	s_barrier
	s_add_i32 s47, s88, s6
	v_lshl_add_u64 v[204:205], s[40:41], 0, v[0:1]
	s_mov_b32 m0, s47
	ds_read_b128 v[180:183], v178 offset:16384
	ds_read_b128 v[184:187], v178 offset:17408
	ds_read_b128 v[188:191], v178 offset:18432
	ds_read_b128 v[192:195], v178 offset:19456
	ds_read_b128 v[196:199], v178 offset:20480
	ds_read_b128 v[200:203], v178 offset:21504
	ds_read_b128 v[208:211], v178 offset:22528
	ds_read_b128 v[230:233], v178 offset:23552
	global_load_lds_dwordx4 v[204:205], off
	s_add_i32 m0, s47, 0x2000
	s_add_u32 s50, s40, 0x80000
	v_lshl_add_u64 v[212:213], s[40:41], 0, v[154:155]
	s_addc_u32 s51, s41, 0
	s_add_i32 s47, s89, s6
	global_load_lds_dwordx4 v[212:213], off
	v_lshl_add_u64 v[234:235], s[50:51], 0, v[0:1]
	s_mov_b32 m0, s47
	v_lshl_add_u64 v[236:237], s[42:43], 0, v[156:157]
	global_load_lds_dwordx4 v[234:235], off
	s_add_i32 m0, s47, 0x2000
	v_lshl_add_u64 v[234:235], s[50:51], 0, v[154:155]
	global_load_lds_dwordx4 v[234:235], off
	s_mov_b32 m0, s8
	v_lshl_add_u64 v[234:235], s[42:43], 0, v[158:159]
	global_load_lds_dwordx4 v[234:235], off
	s_mov_b32 m0, s9
	s_nop 0
	global_load_lds_dwordx4 v[236:237], off
	s_waitcnt vmcnt(8)
	s_waitcnt lgkmcnt(0)
	s_barrier
; #define PG8_STAGE(bufoff, gbase, voff) do { _Pragma("unroll") for (int _i = 0; _i < 2; ++_i) \
;         __builtin_amdgcn_global_load_lds((const unsigned*)((const char*)(gbase) + (voff)[_i]), (PG8_LAS unsigned*)(lds + (bufoff) + ldsw + _i * 8192), 16, 0, 0); } while (0)
; #define PG8_LDA(dst, b, h) do { _Pragma("unroll") for (int m = 0; m < 4; ++m) _Pragma("unroll") for (int k = 0; k < 2; ++k) dst[m][k] = *(const PG8_LAS bf16x8*)(lds + PG8_SA(b, h) + aoff + m * 2048 + k * 1024); } while (0)
; #define PG8_LDB(dst, b, h) do { _Pragma("unroll") for (int n = 0; n < 2; ++n) _Pragma("unroll") for (int k = 0; k < 2; ++k) dst[n][k] = *(const PG8_LAS bf16x8*)(lds + PG8_SB(b, h) + boff + n * 2048 + k * 1024); } while (0)
; #define PG8_MMA(ai, bj, At, Bt) do { __builtin_amdgcn_s_setprio(1); _Pragma("unroll") for (int m = 0; m < 4; ++m) _Pragma("unroll") for (int n = 0; n < 2; ++n) _Pragma("unroll") for (int k = 0; k < 2; ++k) \
;         acc[ai][bj][m][n] = __builtin_amdgcn_mfma_f32_16x16x32_bf16(Bt[n][k], At[m][k], acc[ai][bj][m][n], 0, 0, 0); __builtin_amdgcn_s_setprio(0); } while (0)
; #define PG8_WAIT_V(n) asm volatile("s_waitcnt vmcnt(" #n ")" ::: "memory")
; #define PG8_WAIT_L(n) asm volatile("s_waitcnt lgkmcnt(" #n ")" ::: "memory")
; #define PG8_BAR __builtin_amdgcn_s_barrier()
; #define PG8_SCHED __builtin_amdgcn_sched_barrier(0)
; template <class Epi, class Sched, bool ALIGN_EPI = false, bool SP2 = false>
; __device__ __forceinline__ void gemm_phase(PG8_LAS unsigned char* lds, const Gemm g, const Sched& S, const Epi& E) {
;     ...
;             PG8_WAIT_V(8); PG8_WAIT_L(0); PG8_BAR; PG8_MMA(1, 0, At, B0); PG8_MMA(1, 1, At, B1); PG8_BAR; PG8_SCHED;
;             PG8_LDB(B0, 1, 0); PG8_LDB(B1, 1, 1); PG8_SCHED; PG8_LDA(At, 1, 0); PG8_STAGE(PG8_SA(0, 1), a2 + hstep, voffA);
;             PG8_WAIT_V(8); PG8_WAIT_L(0); PG8_BAR; PG8_MMA(0, 0, At, B0); PG8_MMA(0, 1, At, B1); PG8_BAR; PG8_SCHED;
	s_setprio 1
	v_mfma_f32_16x16x32_bf16 v[62:65], v[114:117], v[180:183], v[62:65]
	v_mfma_f32_16x16x32_bf16 v[58:61], v[130:133], v[180:183], v[58:61]
	v_mfma_f32_16x16x32_bf16 v[46:49], v[114:117], v[188:191], v[46:49]
	v_mfma_f32_16x16x32_bf16 v[42:45], v[130:133], v[188:191], v[42:45]
	v_mfma_f32_16x16x32_bf16 v[30:33], v[114:117], v[196:199], v[30:33]
	v_mfma_f32_16x16x32_bf16 v[26:29], v[130:133], v[196:199], v[26:29]
	v_mfma_f32_16x16x32_bf16 v[14:17], v[114:117], v[208:211], v[14:17]
	v_mfma_f32_16x16x32_bf16 v[10:13], v[130:133], v[208:211], v[10:13]
	v_mfma_f32_16x16x32_bf16 v[62:65], v[118:121], v[184:187], v[62:65]
	v_mfma_f32_16x16x32_bf16 v[58:61], v[134:137], v[184:187], v[58:61]
	v_mfma_f32_16x16x32_bf16 v[46:49], v[118:121], v[192:195], v[46:49]
	v_mfma_f32_16x16x32_bf16 v[42:45], v[134:137], v[192:195], v[42:45]
	v_mfma_f32_16x16x32_bf16 v[30:33], v[118:121], v[200:203], v[30:33]
	v_mfma_f32_16x16x32_bf16 v[26:29], v[134:137], v[200:203], v[26:29]
	v_mfma_f32_16x16x32_bf16 v[14:17], v[118:121], v[230:233], v[14:17]
	v_mfma_f32_16x16x32_bf16 v[10:13], v[134:137], v[230:233], v[10:13]
	v_mfma_f32_16x16x32_bf16 v[54:57], v[146:149], v[180:183], v[54:57]
	v_mfma_f32_16x16x32_bf16 v[50:53], v[168:171], v[180:183], v[50:53]
	v_mfma_f32_16x16x32_bf16 v[38:41], v[146:149], v[188:191], v[38:41]
	v_mfma_f32_16x16x32_bf16 v[34:37], v[168:171], v[188:191], v[34:37]
	v_mfma_f32_16x16x32_bf16 v[22:25], v[146:149], v[196:199], v[22:25]
	v_mfma_f32_16x16x32_bf16 v[18:21], v[168:171], v[196:199], v[18:21]
	v_mfma_f32_16x16x32_bf16 v[6:9], v[146:149], v[208:211], v[6:9]
	v_mfma_f32_16x16x32_bf16 v[2:5], v[168:171], v[208:211], v[2:5]
	v_mfma_f32_16x16x32_bf16 v[54:57], v[150:153], v[184:187], v[54:57]
	v_mfma_f32_16x16x32_bf16 v[50:53], v[172:175], v[184:187], v[50:53]
	v_mfma_f32_16x16x32_bf16 v[38:41], v[150:153], v[192:195], v[38:41]
	v_mfma_f32_16x16x32_bf16 v[34:37], v[172:175], v[192:195], v[34:37]
	v_mfma_f32_16x16x32_bf16 v[22:25], v[150:153], v[200:203], v[22:25]
	v_mfma_f32_16x16x32_bf16 v[18:21], v[172:175], v[200:203], v[18:21]
	v_mfma_f32_16x16x32_bf16 v[6:9], v[150:153], v[230:233], v[6:9]
	v_mfma_f32_16x16x32_bf16 v[2:5], v[172:175], v[230:233], v[2:5]
	s_setprio 0
	s_barrier
	s_add_i32 s47, 0, 0x1c000
	v_add_u32_e32 v134, s90, v177
	v_add_u32_e32 v172, s47, v177
	ds_read_b128 v[114:117], v134
	ds_read_b128 v[118:121], v134 offset:1024
	ds_read_b128 v[130:133], v134 offset:2048
	ds_read_b128 v[134:137], v134 offset:3072
	ds_read_b128 v[146:149], v172
	ds_read_b128 v[150:153], v172 offset:1024
	ds_read_b128 v[168:171], v172 offset:2048
	ds_read_b128 v[172:175], v172 offset:3072
	s_add_u32 s42, s42, 0x80000
	s_addc_u32 s43, s43, 0
	s_mov_b32 m0, s10
	v_lshl_add_u64 v[238:239], s[42:43], 0, v[158:159]
	ds_read_b128 v[180:183], v178 offset:32768
	ds_read_b128 v[184:187], v178 offset:33792
	ds_read_b128 v[188:191], v178 offset:34816
	ds_read_b128 v[192:195], v178 offset:35840
	ds_read_b128 v[196:199], v178 offset:36864
	ds_read_b128 v[200:203], v178 offset:37888
	ds_read_b128 v[208:211], v178 offset:38912
	ds_read_b128 v[230:233], v178 offset:39936
	global_load_lds_dwordx4 v[238:239], off
	s_mov_b32 m0, s11
	v_lshl_add_u64 v[238:239], s[42:43], 0, v[156:157]
	global_load_lds_dwordx4 v[238:239], off
	s_waitcnt vmcnt(8)
	s_waitcnt lgkmcnt(0)
	s_barrier
	s_setprio 1
	v_mfma_f32_16x16x32_bf16 v[142:145], v[114:117], v[180:183], v[142:145]
	v_mfma_f32_16x16x32_bf16 v[138:141], v[130:133], v[180:183], v[138:141]
	v_mfma_f32_16x16x32_bf16 v[110:113], v[114:117], v[188:191], v[110:113]
	v_mfma_f32_16x16x32_bf16 v[106:109], v[130:133], v[188:191], v[106:109]
	v_mfma_f32_16x16x32_bf16 v[94:97], v[114:117], v[196:199], v[94:97]
	v_mfma_f32_16x16x32_bf16 v[90:93], v[130:133], v[196:199], v[90:93]
	v_mfma_f32_16x16x32_bf16 v[78:81], v[114:117], v[208:211], v[78:81]
	v_mfma_f32_16x16x32_bf16 v[74:77], v[130:133], v[208:211], v[74:77]
	v_mfma_f32_16x16x32_bf16 v[142:145], v[118:121], v[184:187], v[142:145]
	v_mfma_f32_16x16x32_bf16 v[138:141], v[134:137], v[184:187], v[138:141]
	v_mfma_f32_16x16x32_bf16 v[110:113], v[118:121], v[192:195], v[110:113]
	v_mfma_f32_16x16x32_bf16 v[106:109], v[134:137], v[192:195], v[106:109]
	v_mfma_f32_16x16x32_bf16 v[94:97], v[118:121], v[200:203], v[94:97]
	v_mfma_f32_16x16x32_bf16 v[90:93], v[134:137], v[200:203], v[90:93]
	v_mfma_f32_16x16x32_bf16 v[78:81], v[118:121], v[230:233], v[78:81]
	v_mfma_f32_16x16x32_bf16 v[74:77], v[134:137], v[230:233], v[74:77]
	v_mfma_f32_16x16x32_bf16 v[126:129], v[146:149], v[180:183], v[126:129]
	v_mfma_f32_16x16x32_bf16 v[122:125], v[168:171], v[180:183], v[122:125]
	v_mfma_f32_16x16x32_bf16 v[102:105], v[146:149], v[188:191], v[102:105]
	v_mfma_f32_16x16x32_bf16 v[98:101], v[168:171], v[188:191], v[98:101]
	v_mfma_f32_16x16x32_bf16 v[86:89], v[146:149], v[196:199], v[86:89]
	v_mfma_f32_16x16x32_bf16 v[82:85], v[168:171], v[196:199], v[82:85]
	v_mfma_f32_16x16x32_bf16 v[70:73], v[146:149], v[208:211], v[70:73]
	v_mfma_f32_16x16x32_bf16 v[66:69], v[168:171], v[208:211], v[66:69]
	v_mfma_f32_16x16x32_bf16 v[126:129], v[150:153], v[184:187], v[126:129]
	v_mfma_f32_16x16x32_bf16 v[122:125], v[172:175], v[184:187], v[122:125]
	v_mfma_f32_16x16x32_bf16 v[102:105], v[150:153], v[192:195], v[102:105]
	v_mfma_f32_16x16x32_bf16 v[98:101], v[172:175], v[192:195], v[98:101]
	v_mfma_f32_16x16x32_bf16 v[86:89], v[150:153], v[200:203], v[86:89]
	v_mfma_f32_16x16x32_bf16 v[82:85], v[172:175], v[200:203], v[82:85]
	v_mfma_f32_16x16x32_bf16 v[70:73], v[150:153], v[230:233], v[70:73]
	v_mfma_f32_16x16x32_bf16 v[66:69], v[172:175], v[230:233], v[66:69]
	s_setprio 0
	s_barrier
; #define PG8_STAGE(bufoff, gbase, voff) do { _Pragma("unroll") for (int _i = 0; _i < 2; ++_i) \
;         __builtin_amdgcn_global_load_lds((const unsigned*)((const char*)(gbase) + (voff)[_i]), (PG8_LAS unsigned*)(lds + (bufoff) + ldsw + _i * 8192), 16, 0, 0); } while (0)
; #define PG8_LDA(dst, b, h) do { _Pragma("unroll") for (int m = 0; m < 4; ++m) _Pragma("unroll") for (int k = 0; k < 2; ++k) dst[m][k] = *(const PG8_LAS bf16x8*)(lds + PG8_SA(b, h) + aoff + m * 2048 + k * 1024); } while (0)
; #define PG8_MMA(ai, bj, At, Bt) do { __builtin_amdgcn_s_setprio(1); _Pragma("unroll") for (int m = 0; m < 4; ++m) _Pragma("unroll") for (int n = 0; n < 2; ++n) _Pragma("unroll") for (int k = 0; k < 2; ++k) \
;         acc[ai][bj][m][n] = __builtin_amdgcn_mfma_f32_16x16x32_bf16(Bt[n][k], At[m][k], acc[ai][bj][m][n], 0, 0, 0); __builtin_amdgcn_s_setprio(0); } while (0)
; #define PG8_WAIT_V(n) asm volatile("s_waitcnt vmcnt(" #n ")" ::: "memory")
; #define PG8_WAIT_L(n) asm volatile("s_waitcnt lgkmcnt(" #n ")" ::: "memory")
; #define PG8_BAR __builtin_amdgcn_s_barrier()
; #define PG8_SCHED __builtin_amdgcn_sched_barrier(0)
; template <class Epi, class Sched, bool ALIGN_EPI = false, bool SP2 = false>
; __device__ __forceinline__ void gemm_phase(PG8_LAS unsigned char* lds, const Gemm g, const Sched& S, const Epi& E) {
;     ...
;             PG8_WAIT_V(8); PG8_WAIT_L(0); PG8_BAR; PG8_MMA(0, 0, At, B0); PG8_MMA(0, 1, At, B1); PG8_BAR; PG8_SCHED;
;             PG8_LDA(At, 1, 1); PG8_STAGE(PG8_SB(1, 0), b3, voffB); PG8_STAGE(PG8_SB(1, 1), b3 + hstep, voffB); PG8_STAGE(PG8_SA(1, 0), a3, voffA);
;             PG8_WAIT_V(8); PG8_WAIT_L(0); PG8_BAR; PG8_MMA(1, 0, At, B0); PG8_MMA(1, 1, At, B1); PG8_BAR; PG8_SCHED;
	s_add_i32 s42, s90, s6
	v_lshl_add_u64 v[204:205], v[204:205], 0, s[70:71]
	s_mov_b32 m0, s42
	ds_read_b128 v[180:183], v178 offset:49152
	ds_read_b128 v[184:187], v178 offset:50176
	ds_read_b128 v[188:191], v178 offset:51200
	ds_read_b128 v[192:195], v178 offset:52224
	ds_read_b128 v[196:199], v178 offset:53248
	ds_read_b128 v[200:203], v178 offset:54272
	ds_read_b128 v[208:211], v178 offset:55296
	ds_read_b128 v[230:233], v178 offset:56320
	global_load_lds_dwordx4 v[204:205], off
	s_add_i32 m0, s42, 0x2000
	s_add_u32 s40, s40, 0x80080
	v_lshl_add_u64 v[204:205], v[212:213], 0, s[70:71]
	s_addc_u32 s41, s41, 0
	s_add_i32 s42, s47, s6
	global_load_lds_dwordx4 v[204:205], off
	s_mov_b32 m0, s42
	v_lshl_add_u64 v[204:205], s[40:41], 0, v[0:1]
	global_load_lds_dwordx4 v[204:205], off
	s_add_i32 m0, s42, 0x2000
	v_lshl_add_u64 v[204:205], s[40:41], 0, v[154:155]
	global_load_lds_dwordx4 v[204:205], off
	s_mov_b32 m0, s13
	v_lshl_add_u64 v[204:205], v[234:235], 0, s[70:71]
	global_load_lds_dwordx4 v[204:205], off
	s_mov_b32 m0, s25
	v_lshl_add_u64 v[204:205], v[236:237], 0, s[70:71]
	global_load_lds_dwordx4 v[204:205], off
	s_waitcnt vmcnt(8)
	s_waitcnt lgkmcnt(0)
	s_barrier
	s_setprio 1
	v_mfma_f32_16x16x32_bf16 v[62:65], v[114:117], v[180:183], v[62:65]
	v_mfma_f32_16x16x32_bf16 v[58:61], v[130:133], v[180:183], v[58:61]
	v_mfma_f32_16x16x32_bf16 v[46:49], v[114:117], v[188:191], v[46:49]
	v_mfma_f32_16x16x32_bf16 v[42:45], v[130:133], v[188:191], v[42:45]
	v_mfma_f32_16x16x32_bf16 v[30:33], v[114:117], v[196:199], v[30:33]
	v_mfma_f32_16x16x32_bf16 v[26:29], v[130:133], v[196:199], v[26:29]
	v_mfma_f32_16x16x32_bf16 v[14:17], v[114:117], v[208:211], v[14:17]
	v_mfma_f32_16x16x32_bf16 v[10:13], v[130:133], v[208:211], v[10:13]
	v_mfma_f32_16x16x32_bf16 v[62:65], v[118:121], v[184:187], v[62:65]
	v_mfma_f32_16x16x32_bf16 v[58:61], v[134:137], v[184:187], v[58:61]
	v_mfma_f32_16x16x32_bf16 v[46:49], v[118:121], v[192:195], v[46:49]
	v_mfma_f32_16x16x32_bf16 v[42:45], v[134:137], v[192:195], v[42:45]
	v_mfma_f32_16x16x32_bf16 v[30:33], v[118:121], v[200:203], v[30:33]
	v_mfma_f32_16x16x32_bf16 v[26:29], v[134:137], v[200:203], v[26:29]
	v_mfma_f32_16x16x32_bf16 v[14:17], v[118:121], v[230:233], v[14:17]
	v_mfma_f32_16x16x32_bf16 v[10:13], v[134:137], v[230:233], v[10:13]
	v_mfma_f32_16x16x32_bf16 v[54:57], v[146:149], v[180:183], v[54:57]
	v_mfma_f32_16x16x32_bf16 v[50:53], v[168:171], v[180:183], v[50:53]
	v_mfma_f32_16x16x32_bf16 v[38:41], v[146:149], v[188:191], v[38:41]
	v_mfma_f32_16x16x32_bf16 v[34:37], v[168:171], v[188:191], v[34:37]
	v_mfma_f32_16x16x32_bf16 v[22:25], v[146:149], v[196:199], v[22:25]
	v_mfma_f32_16x16x32_bf16 v[18:21], v[168:171], v[196:199], v[18:21]
	v_mfma_f32_16x16x32_bf16 v[6:9], v[146:149], v[208:211], v[6:9]
	v_mfma_f32_16x16x32_bf16 v[2:5], v[168:171], v[208:211], v[2:5]
	v_mfma_f32_16x16x32_bf16 v[54:57], v[150:153], v[184:187], v[54:57]
	v_mfma_f32_16x16x32_bf16 v[50:53], v[172:175], v[184:187], v[50:53]
	v_mfma_f32_16x16x32_bf16 v[38:41], v[150:153], v[192:195], v[38:41]
	v_mfma_f32_16x16x32_bf16 v[34:37], v[172:175], v[192:195], v[34:37]
	v_mfma_f32_16x16x32_bf16 v[22:25], v[150:153], v[200:203], v[22:25]
	v_mfma_f32_16x16x32_bf16 v[18:21], v[172:175], v[200:203], v[18:21]
	v_mfma_f32_16x16x32_bf16 v[6:9], v[150:153], v[230:233], v[6:9]
	v_mfma_f32_16x16x32_bf16 v[2:5], v[172:175], v[230:233], v[2:5]
	s_setprio 0
	s_barrier
	s_add_i32 s46, s46, 2
	s_add_u32 s34, s34, 0x100
	s_addc_u32 s35, s35, 0
	s_add_u32 s44, s44, 0x100
	s_addc_u32 s45, s45, 0
	s_cmp_gt_u32 s46, 29
	s_cbranch_scc0 .LBB0_214

; #define PG8_STAGE(bufoff, gbase, voff) do { _Pragma("unroll") for (int _i = 0; _i < 2; ++_i) \
;         __builtin_amdgcn_global_load_lds((const unsigned*)((const char*)(gbase) + (voff)[_i]), (PG8_LAS unsigned*)(lds + (bufoff) + ldsw + _i * 8192), 16, 0, 0); } while (0)
; #define PG8_LDA(dst, b, h) do { _Pragma("unroll") for (int m = 0; m < 4; ++m) _Pragma("unroll") for (int k = 0; k < 2; ++k) dst[m][k] = *(const PG8_LAS bf16x8*)(lds + PG8_SA(b, h) + aoff + m * 2048 + k * 1024); } while (0)
; #define PG8_LDB(dst, b, h) do { _Pragma("unroll") for (int n = 0; n < 2; ++n) _Pragma("unroll") for (int k = 0; k < 2; ++k) dst[n][k] = *(const PG8_LAS bf16x8*)(lds + PG8_SB(b, h) + boff + n * 2048 + k * 1024); } while (0)
; #define PG8_MMA(ai, bj, At, Bt) do { __builtin_amdgcn_s_setprio(1); _Pragma("unroll") for (int m = 0; m < 4; ++m) _Pragma("unroll") for (int n = 0; n < 2; ++n) _Pragma("unroll") for (int k = 0; k < 2; ++k) \
;         acc[ai][bj][m][n] = __builtin_amdgcn_mfma_f32_16x16x32_bf16(Bt[n][k], At[m][k], acc[ai][bj][m][n], 0, 0, 0); __builtin_amdgcn_s_setprio(0); } while (0)
; #define PG8_WAIT_V(n) asm volatile("s_waitcnt vmcnt(" #n ")" ::: "memory")
; #define PG8_WAIT_L(n) asm volatile("s_waitcnt lgkmcnt(" #n ")" ::: "memory")
; #define PG8_BAR __builtin_amdgcn_s_barrier()
; #define PG8_SCHED __builtin_amdgcn_sched_barrier(0)
; template <class Epi, class Sched, bool ALIGN_EPI = false, bool SP2 = false>
; __device__ __forceinline__ void gemm_phase(PG8_LAS unsigned char* lds, const Gemm g, const Sched& S, const Epi& E) {
;     ...
;             if constexpr (SP2) {
;             PG8_LDB(B0, 0, 0); PG8_LDB(B1, 0, 1); PG8_SCHED; PG8_LDA(At, 0, 0); PG8_STAGE(PG8_SA(1, 1), a1 + hstep, voffA);
;             PG8_WAIT_V(8); PG8_WAIT_L(0); PG8_BAR; PG8_MMA(0, 0, At, B0); PG8_MMA(0, 1, At, B1); PG8_BAR; PG8_SCHED;
;             PG8_LDA(At, 0, 1); PG8_STAGE(PG8_SB(0, 0), b2, voffB); PG8_STAGE(PG8_SB(0, 1), b2 + hstep, voffB); PG8_STAGE(PG8_SA(0, 0), a2, voffA);
;             PG8_WAIT_V(8); PG8_WAIT_L(0); PG8_BAR; PG8_MMA(1, 0, At, B0); PG8_MMA(1, 1, At, B1); PG8_BAR; PG8_SCHED;
.Ltail_loop:
	v_add_u32_e32 v134, s88, v177
	ds_read_b128 v[114:117], v134
	ds_read_b128 v[118:121], v134 offset:1024
	ds_read_b128 v[130:133], v134 offset:2048
	ds_read_b128 v[134:137], v134 offset:3072
	s_add_u32 s40, s34, 0xfff80080
	s_addc_u32 s41, s35, -1
	s_cmp_eq_u32 s46, 28
	s_cselect_b32 s43, s15, s41
	s_cselect_b32 s42, s19, s40
	s_cselect_b32 s41, s17, s45
	s_cselect_b32 s40, s37, s44
	v_lshl_add_u64 v[204:205], s[34:35], 0, v[164:165]
	s_add_i32 m0, s8, 0xc000
	ds_read_b128 v[180:183], v178
	ds_read_b128 v[184:187], v178 offset:1024
	ds_read_b128 v[188:191], v178 offset:2048
	ds_read_b128 v[192:195], v178 offset:3072
	ds_read_b128 v[196:199], v178 offset:4096
	ds_read_b128 v[200:203], v178 offset:5120
	ds_read_b128 v[208:211], v178 offset:6144
	ds_read_b128 v[230:233], v178 offset:7168
	global_load_lds_dwordx4 v[204:205], off
	s_add_i32 m0, s8, 0xe000
	v_lshl_add_u64 v[204:205], s[34:35], 0, v[166:167]
	global_load_lds_dwordx4 v[204:205], off
	s_waitcnt vmcnt(8)
	s_waitcnt lgkmcnt(0)
	s_barrier
	s_setprio 1
	v_mfma_f32_16x16x32_bf16 v[142:145], v[114:117], v[180:183], v[142:145]
	v_mfma_f32_16x16x32_bf16 v[138:141], v[130:133], v[180:183], v[138:141]
	v_mfma_f32_16x16x32_bf16 v[110:113], v[114:117], v[188:191], v[110:113]
	v_mfma_f32_16x16x32_bf16 v[106:109], v[130:133], v[188:191], v[106:109]
	v_mfma_f32_16x16x32_bf16 v[94:97], v[114:117], v[196:199], v[94:97]
	v_mfma_f32_16x16x32_bf16 v[90:93], v[130:133], v[196:199], v[90:93]
	v_mfma_f32_16x16x32_bf16 v[78:81], v[114:117], v[208:211], v[78:81]
	v_mfma_f32_16x16x32_bf16 v[74:77], v[130:133], v[208:211], v[74:77]
	v_mfma_f32_16x16x32_bf16 v[142:145], v[118:121], v[184:187], v[142:145]
	v_mfma_f32_16x16x32_bf16 v[138:141], v[134:137], v[184:187], v[138:141]
	v_mfma_f32_16x16x32_bf16 v[110:113], v[118:121], v[192:195], v[110:113]
	v_mfma_f32_16x16x32_bf16 v[106:109], v[134:137], v[192:195], v[106:109]
	v_mfma_f32_16x16x32_bf16 v[94:97], v[118:121], v[200:203], v[94:97]
	v_mfma_f32_16x16x32_bf16 v[90:93], v[134:137], v[200:203], v[90:93]
	v_mfma_f32_16x16x32_bf16 v[78:81], v[118:121], v[230:233], v[78:81]
	v_mfma_f32_16x16x32_bf16 v[74:77], v[134:137], v[230:233], v[74:77]
	s_setprio 0
	s_barrier
	s_add_i32 s47, s88, s6
	v_lshl_add_u64 v[204:205], s[40:41], 0, v[0:1]
	s_mov_b32 m0, s47
	ds_read_b128 v[180:183], v178 offset:16384
	ds_read_b128 v[184:187], v178 offset:17408
	ds_read_b128 v[188:191], v178 offset:18432
	ds_read_b128 v[192:195], v178 offset:19456
	ds_read_b128 v[196:199], v178 offset:20480
	ds_read_b128 v[200:203], v178 offset:21504
	ds_read_b128 v[208:211], v178 offset:22528
	ds_read_b128 v[230:233], v178 offset:23552
	global_load_lds_dwordx4 v[204:205], off
	s_add_i32 m0, s47, 0x2000
	s_add_u32 s50, s40, 0x80000
	v_lshl_add_u64 v[212:213], s[40:41], 0, v[154:155]
	s_addc_u32 s51, s41, 0
	s_add_i32 s47, s89, s6
	global_load_lds_dwordx4 v[212:213], off
	v_lshl_add_u64 v[234:235], s[50:51], 0, v[0:1]
	s_mov_b32 m0, s47
	v_lshl_add_u64 v[236:237], s[42:43], 0, v[156:157]
	global_load_lds_dwordx4 v[234:235], off
	s_add_i32 m0, s47, 0x2000
	v_lshl_add_u64 v[234:235], s[50:51], 0, v[154:155]
	global_load_lds_dwordx4 v[234:235], off
	s_mov_b32 m0, s8
	v_lshl_add_u64 v[234:235], s[42:43], 0, v[158:159]
	global_load_lds_dwordx4 v[234:235], off
	s_mov_b32 m0, s9
	s_nop 0
	global_load_lds_dwordx4 v[236:237], off
	s_waitcnt vmcnt(8)
	s_waitcnt lgkmcnt(0)
	s_barrier
	s_setprio 1
	v_mfma_f32_16x16x32_bf16 v[62:65], v[114:117], v[180:183], v[62:65]
	v_mfma_f32_16x16x32_bf16 v[58:61], v[130:133], v[180:183], v[58:61]
	v_mfma_f32_16x16x32_bf16 v[46:49], v[114:117], v[188:191], v[46:49]
	v_mfma_f32_16x16x32_bf16 v[42:45], v[130:133], v[188:191], v[42:45]
	v_mfma_f32_16x16x32_bf16 v[30:33], v[114:117], v[196:199], v[30:33]
	v_mfma_f32_16x16x32_bf16 v[26:29], v[130:133], v[196:199], v[26:29]
	v_mfma_f32_16x16x32_bf16 v[14:17], v[114:117], v[208:211], v[14:17]
	v_mfma_f32_16x16x32_bf16 v[10:13], v[130:133], v[208:211], v[10:13]
	v_mfma_f32_16x16x32_bf16 v[62:65], v[118:121], v[184:187], v[62:65]
	v_mfma_f32_16x16x32_bf16 v[58:61], v[134:137], v[184:187], v[58:61]
	v_mfma_f32_16x16x32_bf16 v[46:49], v[118:121], v[192:195], v[46:49]
	v_mfma_f32_16x16x32_bf16 v[42:45], v[134:137], v[192:195], v[42:45]
	v_mfma_f32_16x16x32_bf16 v[30:33], v[118:121], v[200:203], v[30:33]
	v_mfma_f32_16x16x32_bf16 v[26:29], v[134:137], v[200:203], v[26:29]
	v_mfma_f32_16x16x32_bf16 v[14:17], v[118:121], v[230:233], v[14:17]
	v_mfma_f32_16x16x32_bf16 v[10:13], v[134:137], v[230:233], v[10:13]
	s_setprio 0
	s_barrier
; #define PG8_STAGE(bufoff, gbase, voff) do { _Pragma("unroll") for (int _i = 0; _i < 2; ++_i) \
;         __builtin_amdgcn_global_load_lds((const unsigned*)((const char*)(gbase) + (voff)[_i]), (PG8_LAS unsigned*)(lds + (bufoff) + ldsw + _i * 8192), 16, 0, 0); } while (0)
; #define PG8_LDA(dst, b, h) do { _Pragma("unroll") for (int m = 0; m < 4; ++m) _Pragma("unroll") for (int k = 0; k < 2; ++k) dst[m][k] = *(const PG8_LAS bf16x8*)(lds + PG8_SA(b, h) + aoff + m * 2048 + k * 1024); } while (0)
; #define PG8_LDB(dst, b, h) do { _Pragma("unroll") for (int n = 0; n < 2; ++n) _Pragma("unroll") for (int k = 0; k < 2; ++k) dst[n][k] = *(const PG8_LAS bf16x8*)(lds + PG8_SB(b, h) + boff + n * 2048 + k * 1024); } while (0)
; #define PG8_MMA(ai, bj, At, Bt) do { __builtin_amdgcn_s_setprio(1); _Pragma("unroll") for (int m = 0; m < 4; ++m) _Pragma("unroll") for (int n = 0; n < 2; ++n) _Pragma("unroll") for (int k = 0; k < 2; ++k) \
;         acc[ai][bj][m][n] = __builtin_amdgcn_mfma_f32_16x16x32_bf16(Bt[n][k], At[m][k], acc[ai][bj][m][n], 0, 0, 0); __builtin_amdgcn_s_setprio(0); } while (0)
; #define PG8_WAIT_V(n) asm volatile("s_waitcnt vmcnt(" #n ")" ::: "memory")
; #define PG8_WAIT_L(n) asm volatile("s_waitcnt lgkmcnt(" #n ")" ::: "memory")
; #define PG8_BAR __builtin_amdgcn_s_barrier()
; #define PG8_SCHED __builtin_amdgcn_sched_barrier(0)
; template <class Epi, class Sched, bool ALIGN_EPI = false, bool SP2 = false>
; __device__ __forceinline__ void gemm_phase(PG8_LAS unsigned char* lds, const Gemm g, const Sched& S, const Epi& E) {
;     ...
;             PG8_LDB(B0, 1, 0); PG8_LDB(B1, 1, 1); PG8_SCHED; PG8_LDA(At, 1, 0); PG8_STAGE(PG8_SA(0, 1), a2 + hstep, voffA);
;             PG8_WAIT_V(8); PG8_WAIT_L(0); PG8_BAR; PG8_MMA(0, 0, At, B0); PG8_MMA(0, 1, At, B1); PG8_BAR; PG8_SCHED;
;             PG8_LDA(At, 1, 1); PG8_STAGE(PG8_SB(1, 0), b3, voffB); PG8_STAGE(PG8_SB(1, 1), b3 + hstep, voffB); PG8_STAGE(PG8_SA(1, 0), a3, voffA);
;             PG8_WAIT_V(8); PG8_WAIT_L(0); PG8_BAR; PG8_MMA(1, 0, At, B0); PG8_MMA(1, 1, At, B1); PG8_BAR; PG8_SCHED;
	s_add_i32 s47, 0, 0x1c000
	v_add_u32_e32 v134, s90, v177
	ds_read_b128 v[114:117], v134
	ds_read_b128 v[118:121], v134 offset:1024
	ds_read_b128 v[130:133], v134 offset:2048
	ds_read_b128 v[134:137], v134 offset:3072
	s_add_u32 s42, s42, 0x80000
	s_addc_u32 s43, s43, 0
	s_mov_b32 m0, s10
	v_lshl_add_u64 v[238:239], s[42:43], 0, v[158:159]
	ds_read_b128 v[180:183], v178 offset:32768
	ds_read_b128 v[184:187], v178 offset:33792
	ds_read_b128 v[188:191], v178 offset:34816
	ds_read_b128 v[192:195], v178 offset:35840
	ds_read_b128 v[196:199], v178 offset:36864
	ds_read_b128 v[200:203], v178 offset:37888
	ds_read_b128 v[208:211], v178 offset:38912
	ds_read_b128 v[230:233], v178 offset:39936
	global_load_lds_dwordx4 v[238:239], off
	s_mov_b32 m0, s11
	v_lshl_add_u64 v[238:239], s[42:43], 0, v[156:157]
	global_load_lds_dwordx4 v[238:239], off
	s_waitcnt vmcnt(8)
	s_waitcnt lgkmcnt(0)
	s_barrier
	s_setprio 1
	v_mfma_f32_16x16x32_bf16 v[142:145], v[114:117], v[180:183], v[142:145]
	v_mfma_f32_16x16x32_bf16 v[138:141], v[130:133], v[180:183], v[138:141]
	v_mfma_f32_16x16x32_bf16 v[110:113], v[114:117], v[188:191], v[110:113]
	v_mfma_f32_16x16x32_bf16 v[106:109], v[130:133], v[188:191], v[106:109]
	v_mfma_f32_16x16x32_bf16 v[94:97], v[114:117], v[196:199], v[94:97]
	v_mfma_f32_16x16x32_bf16 v[90:93], v[130:133], v[196:199], v[90:93]
	v_mfma_f32_16x16x32_bf16 v[78:81], v[114:117], v[208:211], v[78:81]
	v_mfma_f32_16x16x32_bf16 v[74:77], v[130:133], v[208:211], v[74:77]
	v_mfma_f32_16x16x32_bf16 v[142:145], v[118:121], v[184:187], v[142:145]
	v_mfma_f32_16x16x32_bf16 v[138:141], v[134:137], v[184:187], v[138:141]
	v_mfma_f32_16x16x32_bf16 v[110:113], v[118:121], v[192:195], v[110:113]
	v_mfma_f32_16x16x32_bf16 v[106:109], v[134:137], v[192:195], v[106:109]
	v_mfma_f32_16x16x32_bf16 v[94:97], v[118:121], v[200:203], v[94:97]
	v_mfma_f32_16x16x32_bf16 v[90:93], v[134:137], v[200:203], v[90:93]
	v_mfma_f32_16x16x32_bf16 v[78:81], v[118:121], v[230:233], v[78:81]
	v_mfma_f32_16x16x32_bf16 v[74:77], v[134:137], v[230:233], v[74:77]
	s_setprio 0
	s_barrier
	s_add_i32 s42, s90, s6
	v_lshl_add_u64 v[204:205], v[204:205], 0, s[70:71]
	s_mov_b32 m0, s42
	ds_read_b128 v[180:183], v178 offset:49152
	ds_read_b128 v[184:187], v178 offset:50176
	ds_read_b128 v[188:191], v178 offset:51200
	ds_read_b128 v[192:195], v178 offset:52224
	ds_read_b128 v[196:199], v178 offset:53248
	ds_read_b128 v[200:203], v178 offset:54272
	ds_read_b128 v[208:211], v178 offset:55296
	ds_read_b128 v[230:233], v178 offset:56320
	global_load_lds_dwordx4 v[204:205], off
	s_add_i32 m0, s42, 0x2000
	s_add_u32 s40, s40, 0x80080
	v_lshl_add_u64 v[204:205], v[212:213], 0, s[70:71]
	s_addc_u32 s41, s41, 0
	s_add_i32 s42, s47, s6
	global_load_lds_dwordx4 v[204:205], off
	s_mov_b32 m0, s42
	v_lshl_add_u64 v[204:205], s[40:41], 0, v[0:1]
	global_load_lds_dwordx4 v[204:205], off
	s_add_i32 m0, s42, 0x2000
	v_lshl_add_u64 v[204:205], s[40:41], 0, v[154:155]
	global_load_lds_dwordx4 v[204:205], off
	s_mov_b32 m0, s13
	v_lshl_add_u64 v[204:205], v[234:235], 0, s[70:71]
	global_load_lds_dwordx4 v[204:205], off
	s_mov_b32 m0, s25
	v_lshl_add_u64 v[204:205], v[236:237], 0, s[70:71]
	global_load_lds_dwordx4 v[204:205], off
	s_waitcnt vmcnt(8)
	s_waitcnt lgkmcnt(0)
	s_barrier
	s_setprio 1
	v_mfma_f32_16x16x32_bf16 v[62:65], v[114:117], v[180:183], v[62:65]
	v_mfma_f32_16x16x32_bf16 v[58:61], v[130:133], v[180:183], v[58:61]
	v_mfma_f32_16x16x32_bf16 v[46:49], v[114:117], v[188:191], v[46:49]
	v_mfma_f32_16x16x32_bf16 v[42:45], v[130:133], v[188:191], v[42:45]
	v_mfma_f32_16x16x32_bf16 v[30:33], v[114:117], v[196:199], v[30:33]
	v_mfma_f32_16x16x32_bf16 v[26:29], v[130:133], v[196:199], v[26:29]
	v_mfma_f32_16x16x32_bf16 v[14:17], v[114:117], v[208:211], v[14:17]
	v_mfma_f32_16x16x32_bf16 v[10:13], v[130:133], v[208:211], v[10:13]
	v_mfma_f32_16x16x32_bf16 v[62:65], v[118:121], v[184:187], v[62:65]
	v_mfma_f32_16x16x32_bf16 v[58:61], v[134:137], v[184:187], v[58:61]
	v_mfma_f32_16x16x32_bf16 v[46:49], v[118:121], v[192:195], v[46:49]
	v_mfma_f32_16x16x32_bf16 v[42:45], v[134:137], v[192:195], v[42:45]
	v_mfma_f32_16x16x32_bf16 v[30:33], v[118:121], v[200:203], v[30:33]
	v_mfma_f32_16x16x32_bf16 v[26:29], v[134:137], v[200:203], v[26:29]
	v_mfma_f32_16x16x32_bf16 v[14:17], v[118:121], v[230:233], v[14:17]
	v_mfma_f32_16x16x32_bf16 v[10:13], v[134:137], v[230:233], v[10:13]
	s_setprio 0
	s_barrier
	s_add_i32 s46, s46, 2
	s_add_u32 s34, s34, 0x100
	s_addc_u32 s35, s35, 0
	s_add_u32 s44, s44, 0x100
	s_addc_u32 s45, s45, 0
	s_cmp_gt_u32 s46, 29
	s_cbranch_scc0 .Ltail_loop
	s_branch .Ltail_join
